# v66 plus X conversion fused into first norm, counted vmcnt waits in scan staging, de-serialized 4th row load in second norm instance
# speedup vs baseline: 1.0018x; 1.0015x over previous
.LBB0_452:
	s_mov_b32 s4, 0xfa000000
	v_add_co_u32_e32 v86, vcc, s4, v78
	s_mov_b32 s4, 0xfa001000
	s_nop 0
	v_addc_co_u32_e32 v87, vcc, -1, v79, vcc
	global_load_dwordx4 v[88:91], v[86:87], off
	v_add_co_u32_e32 v114, vcc, s4, v78
	s_add_i32 s15, s15, s8
	s_nop 0
	v_addc_co_u32_e32 v115, vcc, -1, v79, vcc
	global_load_dwordx4 v[110:113], v[114:115], off offset:-2048
	s_cmpk_lt_i32 s15, 0x3000
	global_load_dwordx4 v[118:121], v[114:115], off offset:-1024
	global_load_dwordx4 v[124:127], v[114:115], off offset:-3072
	s_waitcnt vmcnt(0)
	v_lshlrev_b32_e32 v100, 16, v88
	v_and_b32_e32 v101, 0xffff0000, v88
	v_lshlrev_b32_e32 v98, 16, v89
	v_and_b32_e32 v99, 0xffff0000, v89
	v_lshlrev_b32_e32 v88, 16, v90
	v_and_b32_e32 v89, 0xffff0000, v90
	v_lshlrev_b32_e32 v86, 16, v91
	v_and_b32_e32 v87, 0xffff0000, v91
	v_lshlrev_b32_e32 v94, 16, v112
	v_and_b32_e32 v95, 0xffff0000, v112
	v_and_b32_e32 v107, 0xffff0000, v110
	v_and_b32_e32 v103, 0xffff0000, v111
	v_lshlrev_b32_e32 v106, 16, v110
	v_lshlrev_b32_e32 v102, 16, v111
	v_lshlrev_b32_e32 v116, 16, v118
	v_and_b32_e32 v117, 0xffff0000, v118
	v_lshlrev_b32_e32 v114, 16, v119
	v_and_b32_e32 v115, 0xffff0000, v119
	v_mul_f32_e32 v118, v101, v101
	v_mul_f32_e32 v119, v99, v99
	v_lshlrev_b32_e32 v112, 16, v120
	v_and_b32_e32 v111, 0xffff0000, v121
	v_lshlrev_b32_e32 v110, 16, v121
	v_fmac_f32_e32 v118, v100, v100
	v_fmac_f32_e32 v119, v98, v98
	v_add_f32_e32 v118, v118, v119
	v_mul_f32_e32 v119, v89, v89
	v_fmac_f32_e32 v119, v88, v88
	s_waitcnt vmcnt(0)
	v_lshlrev_b32_e32 v108, 16, v124
	v_and_b32_e32 v109, 0xffff0000, v124
	v_lshlrev_b32_e32 v104, 16, v125
	v_and_b32_e32 v105, 0xffff0000, v125
	v_lshlrev_b32_e32 v90, 16, v113
	v_and_b32_e32 v91, 0xffff0000, v113
	v_and_b32_e32 v113, 0xffff0000, v120
	v_mul_f32_e32 v120, v87, v87
	v_fmac_f32_e32 v120, v86, v86
	v_add_f32_e32 v119, v119, v120
	v_add_f32_e32 v118, v118, v119
	v_mul_f32_e32 v119, v109, v109
	v_mul_f32_e32 v120, v105, v105
	v_fmac_f32_e32 v119, v108, v108
	v_fmac_f32_e32 v120, v104, v104
	v_lshlrev_b32_e32 v96, 16, v126
	v_and_b32_e32 v97, 0xffff0000, v126
	v_lshlrev_b32_e32 v92, 16, v127
	v_and_b32_e32 v93, 0xffff0000, v127
	v_add_f32_e32 v119, v119, v120
	v_add_f32_e32 v118, v118, v119
	v_mul_f32_e32 v119, v97, v97
	v_mul_f32_e32 v120, v93, v93
	v_fmac_f32_e32 v119, v96, v96
	v_fmac_f32_e32 v120, v92, v92
	v_add_f32_e32 v119, v119, v120
	v_add_f32_e32 v118, v119, v118
	v_mul_f32_e32 v119, v107, v107
	v_mul_f32_e32 v120, v103, v103
	v_fmac_f32_e32 v119, v106, v106
	v_fmac_f32_e32 v120, v102, v102
	v_add_f32_e32 v119, v119, v120
	v_add_f32_e32 v118, v119, v118
	v_mul_f32_e32 v119, v95, v95
	v_mul_f32_e32 v120, v91, v91
	v_fmac_f32_e32 v119, v94, v94
	v_fmac_f32_e32 v120, v90, v90
	v_add_f32_e32 v119, v119, v120
	v_add_f32_e32 v118, v119, v118
	v_mul_f32_e32 v119, v117, v117
	v_mul_f32_e32 v120, v115, v115
	v_fmac_f32_e32 v119, v116, v116
	v_fmac_f32_e32 v120, v114, v114
	v_add_f32_e32 v119, v119, v120
	v_add_f32_e32 v118, v119, v118
	v_mul_f32_e32 v119, v113, v113
	v_mul_f32_e32 v120, v111, v111
	v_fmac_f32_e32 v119, v112, v112
	v_fmac_f32_e32 v120, v110, v110
	v_add_f32_e32 v119, v119, v120
	v_add_f32_e32 v118, v119, v118
	s_nop 1
	v_add_f32_dpp v118, v118, v118 quad_perm:[1,0,3,2] row_mask:0xf bank_mask:0xf bound_ctrl:1
	s_nop 1
	v_add_f32_dpp v118, v118, v118 quad_perm:[2,3,0,1] row_mask:0xf bank_mask:0xf bound_ctrl:1
	s_nop 1
	v_add_f32_dpp v118, v118, v118 row_half_mirror row_mask:0xf bank_mask:0xf bound_ctrl:1
	s_nop 1
	v_add_f32_dpp v118, v118, v118 row_mirror row_mask:0xf bank_mask:0xf bound_ctrl:1
	ds_swizzle_b32 v119, v118 offset:swizzle(SWAP,16)
	s_waitcnt lgkmcnt(0)
	v_add_f32_e32 v118, v118, v119
	v_mov_b32_e32 v119, v118
	s_nop 1
	v_permlane32_swap_b32_e32 v118, v119
	v_add_f32_e32 v118, v118, v119
	v_fmamk_f32 v118, v118, 0x3a000000, v225
	v_cmp_gt_f32_e32 vcc, s91, v118
	v_mul_f32_e32 v119, 0x4f800000, v118
	s_nop 0
	v_cndmask_b32_e32 v118, v118, v119, vcc
	v_sqrt_f32_e32 v119, v118
	s_nop 0
	v_add_u32_e32 v120, -1, v119
	v_fma_f32 v121, -v120, v119, v118
	v_cmp_ge_f32_e64 s[4:5], 0, v121
	v_add_u32_e32 v121, 1, v119
	s_nop 0
	v_cndmask_b32_e64 v120, v119, v120, s[4:5]
	v_fma_f32 v119, -v121, v119, v118
	v_cmp_lt_f32_e64 s[4:5], 0, v119
	s_nop 1
	v_cndmask_b32_e64 v119, v120, v121, s[4:5]
	v_mul_f32_e32 v120, 0x37800000, v119
	v_cndmask_b32_e32 v119, v119, v120, vcc
	v_cmp_class_f32_e32 vcc, v118, v227
	s_nop 1
	v_cndmask_b32_e32 v118, v119, v118, vcc
	v_div_scale_f32 v119, s[4:5], v118, v118, 1.0
	v_rcp_f32_e32 v120, v119
	s_nop 0
	v_fma_f32 v121, -v119, v120, 1.0
	v_fmac_f32_e32 v120, v121, v120
	v_div_scale_f32 v121, vcc, 1.0, v118, 1.0
	v_mul_f32_e32 v122, v121, v120
	v_fma_f32 v123, -v119, v122, v121
	v_fmac_f32_e32 v122, v123, v120
	v_fma_f32 v119, -v119, v122, v121
	v_div_fmas_f32 v119, v119, v120, v122
	v_div_fixup_f32 v118, v119, v118, 1.0
	v_pk_mul_f32 v[88:89], v[88:89], v[118:119] op_sel_hi:[1,0]
	v_pk_mul_f32 v[100:101], v[100:101], v[118:119] op_sel_hi:[1,0]
	v_pk_mul_f32 v[98:99], v[98:99], v[118:119] op_sel_hi:[1,0]
	v_pk_mul_f32 v[86:87], v[86:87], v[118:119] op_sel_hi:[1,0]
	v_pk_fma_f32 v[88:89], v[36:37], v[88:89], v[12:13]
	v_pk_fma_f32 v[98:99], v[34:35], v[98:99], v[2:3]
	v_pk_fma_f32 v[100:101], v[32:33], v[100:101], v[0:1]
	v_pk_fma_f32 v[120:121], v[38:39], v[86:87], v[14:15]
	s_nop 0
	v_cvt_pk_bf16_f32 v86, v100, v101
	s_nop 0
	v_cvt_pk_bf16_f32 v87, v98, v99
	s_nop 0
	v_cvt_pk_bf16_f32 v88, v88, v89
	v_pk_mul_f32 v[96:97], v[118:119], v[96:97] op_sel_hi:[0,1]
	s_nop 0
	v_cvt_pk_bf16_f32 v89, v120, v121
	global_store_dwordx4 v[78:79], v[86:89], off
	v_pk_mul_f32 v[92:93], v[118:119], v[92:93] op_sel_hi:[0,1]
	v_pk_fma_f32 v[92:93], v[46:47], v[92:93], v[6:7]
	v_pk_mul_f32 v[86:87], v[108:109], v[118:119] op_sel_hi:[1,0]
	v_pk_mul_f32 v[88:89], v[104:105], v[118:119] op_sel_hi:[1,0]
	v_pk_fma_f32 v[86:87], v[40:41], v[86:87], v[8:9]
	v_pk_fma_f32 v[88:89], v[42:43], v[88:89], v[10:11]
	v_pk_fma_f32 v[96:97], v[44:45], v[96:97], v[4:5]
	s_nop 0
	v_cvt_pk_bf16_f32 v86, v86, v87
	s_nop 0
	v_cvt_pk_bf16_f32 v87, v88, v89
	v_pk_mul_f32 v[90:91], v[118:119], v[90:91] op_sel_hi:[0,1]
	s_nop 0
	v_cvt_pk_bf16_f32 v88, v96, v97
	s_nop 0
	v_cvt_pk_bf16_f32 v89, v92, v93
	global_store_dwordx4 v[78:79], v[86:89], off offset:1024
	v_pk_mul_f32 v[92:93], v[118:119], v[94:95] op_sel_hi:[0,1]
	v_pk_fma_f32 v[90:91], v[50:51], v[90:91], v[18:19]
	v_pk_mul_f32 v[86:87], v[118:119], v[106:107] op_sel_hi:[0,1]
	v_pk_mul_f32 v[88:89], v[118:119], v[102:103] op_sel_hi:[0,1]
	v_pk_fma_f32 v[88:89], v[62:63], v[88:89], v[26:27]
	v_pk_fma_f32 v[86:87], v[60:61], v[86:87], v[24:25]
	v_pk_fma_f32 v[92:93], v[48:49], v[92:93], v[16:17]
	s_nop 0
	v_cvt_pk_bf16_f32 v86, v86, v87
	s_nop 0
	v_cvt_pk_bf16_f32 v87, v88, v89
	s_nop 0
	s_nop 0
	v_cvt_pk_bf16_f32 v88, v92, v93
	s_nop 0
	v_cvt_pk_bf16_f32 v89, v90, v91
	global_store_dwordx4 v[78:79], v[86:89], off offset:2048
	v_pk_mul_f32 v[90:91], v[118:119], v[112:113] op_sel_hi:[0,1]
	v_pk_mul_f32 v[92:93], v[118:119], v[110:111] op_sel_hi:[0,1]
	v_pk_mul_f32 v[86:87], v[118:119], v[116:117] op_sel_hi:[0,1]
	v_pk_mul_f32 v[88:89], v[118:119], v[114:115] op_sel_hi:[0,1]
	v_pk_fma_f32 v[88:89], v[58:59], v[88:89], v[22:23]
	v_pk_fma_f32 v[86:87], v[56:57], v[86:87], v[20:21]
	v_pk_fma_f32 v[92:93], v[54:55], v[92:93], v[30:31]
	v_pk_fma_f32 v[90:91], v[52:53], v[90:91], v[28:29]
	s_nop 0
	v_cvt_pk_bf16_f32 v86, v86, v87
	s_nop 0
	v_cvt_pk_bf16_f32 v87, v88, v89
	s_nop 0
	s_nop 0
	v_cvt_pk_bf16_f32 v88, v90, v91
	s_nop 0
	v_cvt_pk_bf16_f32 v89, v92, v93
	global_store_dwordx4 v[78:79], v[86:89], off offset:3072
	v_lshl_add_u64 v[78:79], v[78:79], 0, s[10:11]
	s_cbranch_scc0 .LBB0_456
